# hand-written combine phases (rec_combine/diff_combine): 16B loads/stores, 3 rows of loads in flight per wave, 16-lane DPP reductions
# speedup vs baseline: 1.0299x; 1.0205x over previous
; __device__ __forceinline__ int tid_() { int t = threadIdx.x; asm volatile("" : "+v"(t)); return t; }
; __device__ __forceinline__ float bf2f(bf16_t b) { return __uint_as_float(((unsigned)b) << 16); }
; __device__ __forceinline__ bf16_t f2bf(float f) { return (bf16_t)(cvt_pk_bf16(f, 0.f) & 0xffffu); }
; __device__ __forceinline__ void rec_combine(const bf16_t* __restrict__ OF, const bf16_t* __restrict__ OBk, const bf16_t* __restrict__ gate, const float* __restrict__ nw, bf16_t* __restrict__ Y, int coff) {
;   const int tid = tid_(); const int wid = tid >> 6, lane = tid & 63; const float w0 = nw[lane], w1 = nw[64 + lane];
;   const int stride = gridDim.x * 8;
;   for (int r0 = blockIdx.x * 8 + wid; r0 < T_TOK; r0 += 2 * stride)
; #pragma unroll
;   for (int rr = 0; rr < 2; ++rr) { const int r = r0 + rr * stride; if (r >= T_TOK) break;
; #pragma unroll
;     for (int h = 0; h < 4; ++h) { const size_t b = (size_t)r * 512 + h * 128 + lane;
;       const float a0 = bf2f(OF[b]) + bf2f(OBk[b]), a1 = bf2f(OF[b + 64]) + bf2f(OBk[b + 64]);
;       const float ss = wave_sum(a0 * a0 + a1 * a1); const float rs = rsqrtf(ss * (1.f / 128.f) + EPSN);
;       bf16_t* yo = Y + (size_t)r * DM + coff + h * 128 + lane; yo[0] = f2bf(a0 * rs * w0 * bf2f(gate[b])); yo[64] = f2bf(a1 * rs * w1 * bf2f(gate[b + 64])); }
;   }
; }
; __device__ __forceinline__ void diff_combine(const bf16_t* __restrict__ OD, const float* __restrict__ subln, float lam, float one_m_li, bf16_t* __restrict__ Y) {
;   const int tid = tid_(); const int wid = tid >> 6, lane = tid & 63; const float w0 = subln[lane] * one_m_li, w1 = subln[64 + lane] * one_m_li;
;   for (int r = blockIdx.x * 8 + wid; r < T_TOK; r += gridDim.x * 8) {
; #pragma unroll
;     for (int h = 0; h < 4; ++h) { const bf16_t* o1 = OD + (size_t)r * 1024 + h * 256 + lane; const bf16_t* o2 = o1 + 128;
;       const float a0 = bf2f(o1[0]) - lam * bf2f(o2[0]), a1 = bf2f(o1[64]) - lam * bf2f(o2[64]);
;       const float ss = wave_sum(a0 * a0 + a1 * a1); const float rs = rsqrtf(ss * (1.f / 128.f) + EPSN);
;       bf16_t* yo = Y + (size_t)r * DM + h * 128 + lane; yo[0] = f2bf(a0 * rs * w0); yo[64] = f2bf(a1 * rs * w1); }
;   }
; }
.LBB0_1464:
	s_or_b64 exec, exec, s[4:5]
	s_mov_b64 s[6:7], s[0:1]
	s_mov_b64 s[4:5], s[0:1]
	s_waitcnt lgkmcnt(0)
	s_barrier
	s_load_dwordx2 s[4:5], s[0:1], 0xd8
	s_load_dwordx2 s[8:9], s[0:1], 0xb8
	s_load_dwordx2 s[10:11], s[0:1], 0xc8
	v_and_b32_e32 v0, 63, v187
	v_lshlrev_b32_e32 v1, 4, v0
	v_and_b32_e32 v2, 15, v0
	v_lshrrev_b32_e32 v3, 4, v0
	v_lshlrev_b32_e32 v3, 9, v3
	v_lshl_add_u32 v3, v2, 4, v3
	v_lshlrev_b32_e32 v2, 5, v2
	s_lshl_b32 s16, s34, 9
	v_add_u32_e32 v2, s16, v2
	v_readfirstlane_b32 s17, v187
	s_nop 3
	s_lshr_b32 s17, s17, 6
	s_lshl_b32 s16, s2, 3
	s_add_i32 s16, s16, s17
	s_waitcnt lgkmcnt(0)
	global_load_dwordx4 v[4:7], v2, s[8:9]
	global_load_dwordx4 v[8:11], v2, s[8:9] offset:16
	global_load_dwordx4 v[12:15], v2, s[10:11]
	global_load_dwordx4 v[16:19], v2, s[10:11] offset:16
	s_and_b32 s17, s44, 2
	s_lshl_b32 s17, s17, 2
	v_mov_b32_e32 v20, 0x9bca000
	v_add_u32_e32 v21, s17, v20
	s_lshl_b32 s17, s44, 2
	v_add_u32_e32 v22, s17, v20
	global_load_dword v20, v21, s[4:5]
	global_load_dword v21, v22, s[4:5]
	s_add_u32 s6, s4, 0x1158e100
	s_addc_u32 s7, s5, 0
	s_add_u32 s8, s4, 0x4100000
	s_addc_u32 s9, s5, 0
	s_add_u32 s10, s4, 0x5140000
	s_addc_u32 s11, s5, 0
	s_add_u32 s12, s4, 0x1054e100
	s_addc_u32 s13, s5, 0
	s_add_u32 s14, s4, 0x6180000
	s_addc_u32 s15, s5, 0
	s_waitcnt vmcnt(0)
	v_mul_f32_e32 v4, v21, v4
	v_mul_f32_e32 v5, v21, v5
	v_mul_f32_e32 v6, v21, v6
	v_mul_f32_e32 v7, v21, v7
	v_mul_f32_e32 v8, v21, v8
	v_mul_f32_e32 v9, v21, v9
	v_mul_f32_e32 v10, v21, v10
	v_mul_f32_e32 v11, v21, v11
	s_mov_b32 s17, 0
.Lcmb_odd_loop:
	s_min_i32 s4, s16, 0x40ff
	s_lshl_b32 s5, s4, 11
	v_add_u32_e32 v22, s5, v3
	v_add_u32_e32 v24, s5, v1
	s_lshl_b32 s5, s4, 10
	v_add_u32_e32 v23, s5, v1
	s_add_i32 s16, s16, 0x800
	global_load_dwordx4 v[32:35], v22, s[6:7]
	global_load_dwordx4 v[36:39], v22, s[6:7] offset:256
	global_load_dwordx4 v[40:43], v23, s[8:9]
	global_load_dwordx4 v[44:47], v23, s[10:11]
	global_load_dwordx4 v[48:51], v23, s[12:13]
	s_min_i32 s4, s16, 0x40ff
	s_lshl_b32 s5, s4, 11
	v_add_u32_e32 v25, s5, v3
	v_add_u32_e32 v27, s5, v1
	s_lshl_b32 s5, s4, 10
	v_add_u32_e32 v26, s5, v1
	s_add_i32 s16, s16, 0x800
	global_load_dwordx4 v[52:55], v25, s[6:7]
	global_load_dwordx4 v[56:59], v25, s[6:7] offset:256
	global_load_dwordx4 v[60:63], v26, s[8:9]
	global_load_dwordx4 v[64:67], v26, s[10:11]
	global_load_dwordx4 v[68:71], v26, s[12:13]
	s_min_i32 s4, s16, 0x40ff
	s_lshl_b32 s5, s4, 11
	v_add_u32_e32 v28, s5, v3
	v_add_u32_e32 v30, s5, v1
	s_lshl_b32 s5, s4, 10
	v_add_u32_e32 v29, s5, v1
	s_add_i32 s16, s16, 0x800
	global_load_dwordx4 v[72:75], v28, s[6:7]
	global_load_dwordx4 v[76:79], v28, s[6:7] offset:256
	global_load_dwordx4 v[80:83], v29, s[8:9]
	global_load_dwordx4 v[84:87], v29, s[10:11]
	global_load_dwordx4 v[88:91], v29, s[12:13]
	s_waitcnt vmcnt(10)
	v_lshlrev_b32_e32 v96, 16, v32
	v_and_b32_e32 v97, 0xffff0000, v32
	v_lshlrev_b32_e32 v106, 16, v36
	v_and_b32_e32 v107, 0xffff0000, v36
	v_fma_f32 v96, -v20, v106, v96
	v_fma_f32 v97, -v20, v107, v97
	v_lshlrev_b32_e32 v98, 16, v33
	v_and_b32_e32 v99, 0xffff0000, v33
	v_lshlrev_b32_e32 v106, 16, v37
	v_and_b32_e32 v107, 0xffff0000, v37
	v_fma_f32 v98, -v20, v106, v98
	v_fma_f32 v99, -v20, v107, v99
	v_lshlrev_b32_e32 v100, 16, v34
	v_and_b32_e32 v101, 0xffff0000, v34
	v_lshlrev_b32_e32 v106, 16, v38
	v_and_b32_e32 v107, 0xffff0000, v38
	v_fma_f32 v100, -v20, v106, v100
	v_fma_f32 v101, -v20, v107, v101
	v_lshlrev_b32_e32 v102, 16, v35
	v_and_b32_e32 v103, 0xffff0000, v35
	v_lshlrev_b32_e32 v106, 16, v39
	v_and_b32_e32 v107, 0xffff0000, v39
	v_fma_f32 v102, -v20, v106, v102
	v_fma_f32 v103, -v20, v107, v103
	v_mul_f32_e32 v104, v96, v96
	v_fmac_f32_e32 v104, v97, v97
	v_fmac_f32_e32 v104, v98, v98
	v_fmac_f32_e32 v104, v99, v99
	v_fmac_f32_e32 v104, v100, v100
	v_fmac_f32_e32 v104, v101, v101
	v_fmac_f32_e32 v104, v102, v102
	v_fmac_f32_e32 v104, v103, v103
	s_nop 1
	v_add_f32_dpp v104, v104, v104 quad_perm:[1,0,3,2] row_mask:0xf bank_mask:0xf bound_ctrl:1
	s_nop 1
	v_add_f32_dpp v104, v104, v104 quad_perm:[2,3,0,1] row_mask:0xf bank_mask:0xf bound_ctrl:1
	s_nop 1
	v_add_f32_dpp v104, v104, v104 row_ror:4 row_mask:0xf bank_mask:0xf bound_ctrl:1
	s_nop 1
	v_add_f32_dpp v104, v104, v104 row_ror:8 row_mask:0xf bank_mask:0xf bound_ctrl:1
	v_mov_b32_e32 v105, 0x358637bd
	v_fmac_f32_e32 v105, 0x3c000000, v104
	v_rsq_f32_e32 v105, v105
	s_nop 0
	v_mul_f32_e32 v108, v96, v105
	v_mul_f32_e32 v108, v108, v4
	v_mul_f32_e32 v109, v97, v105
	v_mul_f32_e32 v109, v109, v5
	v_mul_f32_e32 v110, v98, v105
	v_mul_f32_e32 v110, v110, v6
	v_mul_f32_e32 v111, v99, v105
	v_mul_f32_e32 v111, v111, v7
	v_mul_f32_e32 v112, v100, v105
	v_mul_f32_e32 v112, v112, v8
	v_mul_f32_e32 v113, v101, v105
	v_mul_f32_e32 v113, v113, v9
	v_mul_f32_e32 v114, v102, v105
	v_mul_f32_e32 v114, v114, v10
	v_mul_f32_e32 v115, v103, v105
	v_mul_f32_e32 v115, v115, v11
	v_cvt_pk_bf16_f32 v120, v108, v109
	v_cvt_pk_bf16_f32 v121, v110, v111
	v_cvt_pk_bf16_f32 v122, v112, v113
	v_cvt_pk_bf16_f32 v123, v114, v115
	global_store_dwordx4 v24, v[120:123], s[14:15]
	s_nop 1
	v_lshlrev_b32_e32 v106, 16, v40
	v_and_b32_e32 v107, 0xffff0000, v40
	v_lshlrev_b32_e32 v96, 16, v44
	v_and_b32_e32 v97, 0xffff0000, v44
	v_add_f32_e32 v96, v106, v96
	v_add_f32_e32 v97, v107, v97
	v_lshlrev_b32_e32 v106, 16, v41
	v_and_b32_e32 v107, 0xffff0000, v41
	v_lshlrev_b32_e32 v98, 16, v45
	v_and_b32_e32 v99, 0xffff0000, v45
	v_add_f32_e32 v98, v106, v98
	v_add_f32_e32 v99, v107, v99
	v_lshlrev_b32_e32 v106, 16, v42
	v_and_b32_e32 v107, 0xffff0000, v42
	v_lshlrev_b32_e32 v100, 16, v46
	v_and_b32_e32 v101, 0xffff0000, v46
; __device__ __forceinline__ int tid_() { int t = threadIdx.x; asm volatile("" : "+v"(t)); return t; }
; __device__ __forceinline__ float bf2f(bf16_t b) { return __uint_as_float(((unsigned)b) << 16); }
; __device__ __forceinline__ bf16_t f2bf(float f) { return (bf16_t)(cvt_pk_bf16(f, 0.f) & 0xffffu); }
; __device__ __forceinline__ void rec_combine(const bf16_t* __restrict__ OF, const bf16_t* __restrict__ OBk, const bf16_t* __restrict__ gate, const float* __restrict__ nw, bf16_t* __restrict__ Y, int coff) {
;   const int tid = tid_(); const int wid = tid >> 6, lane = tid & 63; const float w0 = nw[lane], w1 = nw[64 + lane];
;   const int stride = gridDim.x * 8;
;   for (int r0 = blockIdx.x * 8 + wid; r0 < T_TOK; r0 += 2 * stride)
; #pragma unroll
;   for (int rr = 0; rr < 2; ++rr) { const int r = r0 + rr * stride; if (r >= T_TOK) break;
; #pragma unroll
;     for (int h = 0; h < 4; ++h) { const size_t b = (size_t)r * 512 + h * 128 + lane;
;       const float a0 = bf2f(OF[b]) + bf2f(OBk[b]), a1 = bf2f(OF[b + 64]) + bf2f(OBk[b + 64]);
;       const float ss = wave_sum(a0 * a0 + a1 * a1); const float rs = rsqrtf(ss * (1.f / 128.f) + EPSN);
;       bf16_t* yo = Y + (size_t)r * DM + coff + h * 128 + lane; yo[0] = f2bf(a0 * rs * w0 * bf2f(gate[b])); yo[64] = f2bf(a1 * rs * w1 * bf2f(gate[b + 64])); }
;   }
; }
; __device__ __forceinline__ void diff_combine(const bf16_t* __restrict__ OD, const float* __restrict__ subln, float lam, float one_m_li, bf16_t* __restrict__ Y) {
;   const int tid = tid_(); const int wid = tid >> 6, lane = tid & 63; const float w0 = subln[lane] * one_m_li, w1 = subln[64 + lane] * one_m_li;
;   for (int r = blockIdx.x * 8 + wid; r < T_TOK; r += gridDim.x * 8) {
; #pragma unroll
;     for (int h = 0; h < 4; ++h) { const bf16_t* o1 = OD + (size_t)r * 1024 + h * 256 + lane; const bf16_t* o2 = o1 + 128;
;       const float a0 = bf2f(o1[0]) - lam * bf2f(o2[0]), a1 = bf2f(o1[64]) - lam * bf2f(o2[64]);
;       const float ss = wave_sum(a0 * a0 + a1 * a1); const float rs = rsqrtf(ss * (1.f / 128.f) + EPSN);
;       bf16_t* yo = Y + (size_t)r * DM + h * 128 + lane; yo[0] = f2bf(a0 * rs * w0); yo[64] = f2bf(a1 * rs * w1); }
;   }
; }
	v_add_f32_e32 v100, v106, v100
	v_add_f32_e32 v101, v107, v101
	v_lshlrev_b32_e32 v106, 16, v43
	v_and_b32_e32 v107, 0xffff0000, v43
	v_lshlrev_b32_e32 v102, 16, v47
	v_and_b32_e32 v103, 0xffff0000, v47
	v_add_f32_e32 v102, v106, v102
	v_add_f32_e32 v103, v107, v103
	v_mul_f32_e32 v104, v96, v96
	v_fmac_f32_e32 v104, v97, v97
	v_fmac_f32_e32 v104, v98, v98
	v_fmac_f32_e32 v104, v99, v99
	v_fmac_f32_e32 v104, v100, v100
	v_fmac_f32_e32 v104, v101, v101
	v_fmac_f32_e32 v104, v102, v102
	v_fmac_f32_e32 v104, v103, v103
	s_nop 1
	v_add_f32_dpp v104, v104, v104 quad_perm:[1,0,3,2] row_mask:0xf bank_mask:0xf bound_ctrl:1
	s_nop 1
	v_add_f32_dpp v104, v104, v104 quad_perm:[2,3,0,1] row_mask:0xf bank_mask:0xf bound_ctrl:1
	s_nop 1
	v_add_f32_dpp v104, v104, v104 row_ror:4 row_mask:0xf bank_mask:0xf bound_ctrl:1
	s_nop 1
	v_add_f32_dpp v104, v104, v104 row_ror:8 row_mask:0xf bank_mask:0xf bound_ctrl:1
	v_mov_b32_e32 v105, 0x358637bd
	v_fmac_f32_e32 v105, 0x3c000000, v104
	v_rsq_f32_e32 v105, v105
	s_nop 0
	v_lshlrev_b32_e32 v106, 16, v48
	v_and_b32_e32 v107, 0xffff0000, v48
	v_mul_f32_e32 v108, v96, v105
	v_mul_f32_e32 v108, v12, v108
	v_mul_f32_e32 v108, v108, v106
	v_mul_f32_e32 v109, v97, v105
	v_mul_f32_e32 v109, v13, v109
	v_mul_f32_e32 v109, v109, v107
	v_lshlrev_b32_e32 v106, 16, v49
	v_and_b32_e32 v107, 0xffff0000, v49
	v_mul_f32_e32 v110, v98, v105
	v_mul_f32_e32 v110, v14, v110
	v_mul_f32_e32 v110, v110, v106
	v_mul_f32_e32 v111, v99, v105
	v_mul_f32_e32 v111, v15, v111
	v_mul_f32_e32 v111, v111, v107
	v_lshlrev_b32_e32 v106, 16, v50
	v_and_b32_e32 v107, 0xffff0000, v50
	v_mul_f32_e32 v112, v100, v105
	v_mul_f32_e32 v112, v16, v112
	v_mul_f32_e32 v112, v112, v106
	v_mul_f32_e32 v113, v101, v105
	v_mul_f32_e32 v113, v17, v113
	v_mul_f32_e32 v113, v113, v107
	v_lshlrev_b32_e32 v106, 16, v51
	v_and_b32_e32 v107, 0xffff0000, v51
	v_mul_f32_e32 v114, v102, v105
	v_mul_f32_e32 v114, v18, v114
	v_mul_f32_e32 v114, v114, v106
	v_mul_f32_e32 v115, v103, v105
	v_mul_f32_e32 v115, v19, v115
	v_mul_f32_e32 v115, v115, v107
	v_cvt_pk_bf16_f32 v124, v108, v109
	v_cvt_pk_bf16_f32 v125, v110, v111
	v_cvt_pk_bf16_f32 v126, v112, v113
	v_cvt_pk_bf16_f32 v127, v114, v115
	global_store_dwordx4 v24, v[124:127], s[14:15] offset:1024
	s_nop 1
	s_waitcnt vmcnt(7)
	v_lshlrev_b32_e32 v96, 16, v52
	v_and_b32_e32 v97, 0xffff0000, v52
	v_lshlrev_b32_e32 v106, 16, v56
	v_and_b32_e32 v107, 0xffff0000, v56
	v_fma_f32 v96, -v20, v106, v96
	v_fma_f32 v97, -v20, v107, v97
	v_lshlrev_b32_e32 v98, 16, v53
	v_and_b32_e32 v99, 0xffff0000, v53
	v_lshlrev_b32_e32 v106, 16, v57
	v_and_b32_e32 v107, 0xffff0000, v57
	v_fma_f32 v98, -v20, v106, v98
	v_fma_f32 v99, -v20, v107, v99
	v_lshlrev_b32_e32 v100, 16, v54
	v_and_b32_e32 v101, 0xffff0000, v54
	v_lshlrev_b32_e32 v106, 16, v58
	v_and_b32_e32 v107, 0xffff0000, v58
	v_fma_f32 v100, -v20, v106, v100
	v_fma_f32 v101, -v20, v107, v101
	v_lshlrev_b32_e32 v102, 16, v55
	v_and_b32_e32 v103, 0xffff0000, v55
	v_lshlrev_b32_e32 v106, 16, v59
	v_and_b32_e32 v107, 0xffff0000, v59
	v_fma_f32 v102, -v20, v106, v102
	v_fma_f32 v103, -v20, v107, v103
	v_mul_f32_e32 v104, v96, v96
	v_fmac_f32_e32 v104, v97, v97
	v_fmac_f32_e32 v104, v98, v98
	v_fmac_f32_e32 v104, v99, v99
	v_fmac_f32_e32 v104, v100, v100
	v_fmac_f32_e32 v104, v101, v101
	v_fmac_f32_e32 v104, v102, v102
	v_fmac_f32_e32 v104, v103, v103
	s_nop 1
	v_add_f32_dpp v104, v104, v104 quad_perm:[1,0,3,2] row_mask:0xf bank_mask:0xf bound_ctrl:1
	s_nop 1
	v_add_f32_dpp v104, v104, v104 quad_perm:[2,3,0,1] row_mask:0xf bank_mask:0xf bound_ctrl:1
	s_nop 1
	v_add_f32_dpp v104, v104, v104 row_ror:4 row_mask:0xf bank_mask:0xf bound_ctrl:1
	s_nop 1
	v_add_f32_dpp v104, v104, v104 row_ror:8 row_mask:0xf bank_mask:0xf bound_ctrl:1
	v_mov_b32_e32 v105, 0x358637bd
	v_fmac_f32_e32 v105, 0x3c000000, v104
	v_rsq_f32_e32 v105, v105
	s_nop 0
	v_mul_f32_e32 v108, v96, v105
	v_mul_f32_e32 v108, v108, v4
	v_mul_f32_e32 v109, v97, v105
	v_mul_f32_e32 v109, v109, v5
	v_mul_f32_e32 v110, v98, v105
	v_mul_f32_e32 v110, v110, v6
	v_mul_f32_e32 v111, v99, v105
	v_mul_f32_e32 v111, v111, v7
	v_mul_f32_e32 v112, v100, v105
	v_mul_f32_e32 v112, v112, v8
	v_mul_f32_e32 v113, v101, v105
	v_mul_f32_e32 v113, v113, v9
	v_mul_f32_e32 v114, v102, v105
	v_mul_f32_e32 v114, v114, v10
	v_mul_f32_e32 v115, v103, v105
	v_mul_f32_e32 v115, v115, v11
	v_cvt_pk_bf16_f32 v120, v108, v109
	v_cvt_pk_bf16_f32 v121, v110, v111
	v_cvt_pk_bf16_f32 v122, v112, v113
	v_cvt_pk_bf16_f32 v123, v114, v115
	global_store_dwordx4 v27, v[120:123], s[14:15]
	s_nop 1
	v_lshlrev_b32_e32 v106, 16, v60
	v_and_b32_e32 v107, 0xffff0000, v60
	v_lshlrev_b32_e32 v96, 16, v64
	v_and_b32_e32 v97, 0xffff0000, v64
	v_add_f32_e32 v96, v106, v96
	v_add_f32_e32 v97, v107, v97
	v_lshlrev_b32_e32 v106, 16, v61
	v_and_b32_e32 v107, 0xffff0000, v61
	v_lshlrev_b32_e32 v98, 16, v65
	v_and_b32_e32 v99, 0xffff0000, v65
	v_add_f32_e32 v98, v106, v98
	v_add_f32_e32 v99, v107, v99
	v_lshlrev_b32_e32 v106, 16, v62
	v_and_b32_e32 v107, 0xffff0000, v62
	v_lshlrev_b32_e32 v100, 16, v66
	v_and_b32_e32 v101, 0xffff0000, v66
	v_add_f32_e32 v100, v106, v100
	v_add_f32_e32 v101, v107, v101
	v_lshlrev_b32_e32 v106, 16, v63
	v_and_b32_e32 v107, 0xffff0000, v63
	v_lshlrev_b32_e32 v102, 16, v67
	v_and_b32_e32 v103, 0xffff0000, v67
	v_add_f32_e32 v102, v106, v102
	v_add_f32_e32 v103, v107, v103
	v_mul_f32_e32 v104, v96, v96
	v_fmac_f32_e32 v104, v97, v97
	v_fmac_f32_e32 v104, v98, v98
	v_fmac_f32_e32 v104, v99, v99
	v_fmac_f32_e32 v104, v100, v100
	v_fmac_f32_e32 v104, v101, v101
	v_fmac_f32_e32 v104, v102, v102
	v_fmac_f32_e32 v104, v103, v103
	s_nop 1
; __device__ __forceinline__ int tid_() { int t = threadIdx.x; asm volatile("" : "+v"(t)); return t; }
; __device__ __forceinline__ float bf2f(bf16_t b) { return __uint_as_float(((unsigned)b) << 16); }
; __device__ __forceinline__ bf16_t f2bf(float f) { return (bf16_t)(cvt_pk_bf16(f, 0.f) & 0xffffu); }
; __device__ __forceinline__ void rec_combine(const bf16_t* __restrict__ OF, const bf16_t* __restrict__ OBk, const bf16_t* __restrict__ gate, const float* __restrict__ nw, bf16_t* __restrict__ Y, int coff) {
;   const int tid = tid_(); const int wid = tid >> 6, lane = tid & 63; const float w0 = nw[lane], w1 = nw[64 + lane];
;   const int stride = gridDim.x * 8;
;   for (int r0 = blockIdx.x * 8 + wid; r0 < T_TOK; r0 += 2 * stride)
; #pragma unroll
;   for (int rr = 0; rr < 2; ++rr) { const int r = r0 + rr * stride; if (r >= T_TOK) break;
; #pragma unroll
;     for (int h = 0; h < 4; ++h) { const size_t b = (size_t)r * 512 + h * 128 + lane;
;       const float a0 = bf2f(OF[b]) + bf2f(OBk[b]), a1 = bf2f(OF[b + 64]) + bf2f(OBk[b + 64]);
;       const float ss = wave_sum(a0 * a0 + a1 * a1); const float rs = rsqrtf(ss * (1.f / 128.f) + EPSN);
;       bf16_t* yo = Y + (size_t)r * DM + coff + h * 128 + lane; yo[0] = f2bf(a0 * rs * w0 * bf2f(gate[b])); yo[64] = f2bf(a1 * rs * w1 * bf2f(gate[b + 64])); }
;   }
; }
; __device__ __forceinline__ void diff_combine(const bf16_t* __restrict__ OD, const float* __restrict__ subln, float lam, float one_m_li, bf16_t* __restrict__ Y) {
;   const int tid = tid_(); const int wid = tid >> 6, lane = tid & 63; const float w0 = subln[lane] * one_m_li, w1 = subln[64 + lane] * one_m_li;
;   for (int r = blockIdx.x * 8 + wid; r < T_TOK; r += gridDim.x * 8) {
; #pragma unroll
;     for (int h = 0; h < 4; ++h) { const bf16_t* o1 = OD + (size_t)r * 1024 + h * 256 + lane; const bf16_t* o2 = o1 + 128;
;       const float a0 = bf2f(o1[0]) - lam * bf2f(o2[0]), a1 = bf2f(o1[64]) - lam * bf2f(o2[64]);
;       const float ss = wave_sum(a0 * a0 + a1 * a1); const float rs = rsqrtf(ss * (1.f / 128.f) + EPSN);
;       bf16_t* yo = Y + (size_t)r * DM + h * 128 + lane; yo[0] = f2bf(a0 * rs * w0); yo[64] = f2bf(a1 * rs * w1); }
;   }
; }
	v_add_f32_dpp v104, v104, v104 quad_perm:[1,0,3,2] row_mask:0xf bank_mask:0xf bound_ctrl:1
	s_nop 1
	v_add_f32_dpp v104, v104, v104 quad_perm:[2,3,0,1] row_mask:0xf bank_mask:0xf bound_ctrl:1
	s_nop 1
	v_add_f32_dpp v104, v104, v104 row_ror:4 row_mask:0xf bank_mask:0xf bound_ctrl:1
	s_nop 1
	v_add_f32_dpp v104, v104, v104 row_ror:8 row_mask:0xf bank_mask:0xf bound_ctrl:1
	v_mov_b32_e32 v105, 0x358637bd
	v_fmac_f32_e32 v105, 0x3c000000, v104
	v_rsq_f32_e32 v105, v105
	s_nop 0
	v_lshlrev_b32_e32 v106, 16, v68
	v_and_b32_e32 v107, 0xffff0000, v68
	v_mul_f32_e32 v108, v96, v105
	v_mul_f32_e32 v108, v12, v108
	v_mul_f32_e32 v108, v108, v106
	v_mul_f32_e32 v109, v97, v105
	v_mul_f32_e32 v109, v13, v109
	v_mul_f32_e32 v109, v109, v107
	v_lshlrev_b32_e32 v106, 16, v69
	v_and_b32_e32 v107, 0xffff0000, v69
	v_mul_f32_e32 v110, v98, v105
	v_mul_f32_e32 v110, v14, v110
	v_mul_f32_e32 v110, v110, v106
	v_mul_f32_e32 v111, v99, v105
	v_mul_f32_e32 v111, v15, v111
	v_mul_f32_e32 v111, v111, v107
	v_lshlrev_b32_e32 v106, 16, v70
	v_and_b32_e32 v107, 0xffff0000, v70
	v_mul_f32_e32 v112, v100, v105
	v_mul_f32_e32 v112, v16, v112
	v_mul_f32_e32 v112, v112, v106
	v_mul_f32_e32 v113, v101, v105
	v_mul_f32_e32 v113, v17, v113
	v_mul_f32_e32 v113, v113, v107
	v_lshlrev_b32_e32 v106, 16, v71
	v_and_b32_e32 v107, 0xffff0000, v71
	v_mul_f32_e32 v114, v102, v105
	v_mul_f32_e32 v114, v18, v114
	v_mul_f32_e32 v114, v114, v106
	v_mul_f32_e32 v115, v103, v105
	v_mul_f32_e32 v115, v19, v115
	v_mul_f32_e32 v115, v115, v107
	v_cvt_pk_bf16_f32 v124, v108, v109
	v_cvt_pk_bf16_f32 v125, v110, v111
	v_cvt_pk_bf16_f32 v126, v112, v113
	v_cvt_pk_bf16_f32 v127, v114, v115
	global_store_dwordx4 v27, v[124:127], s[14:15] offset:1024
	s_nop 1
	s_waitcnt vmcnt(4)
	v_lshlrev_b32_e32 v96, 16, v72
	v_and_b32_e32 v97, 0xffff0000, v72
	v_lshlrev_b32_e32 v106, 16, v76
	v_and_b32_e32 v107, 0xffff0000, v76
	v_fma_f32 v96, -v20, v106, v96
	v_fma_f32 v97, -v20, v107, v97
	v_lshlrev_b32_e32 v98, 16, v73
	v_and_b32_e32 v99, 0xffff0000, v73
	v_lshlrev_b32_e32 v106, 16, v77
	v_and_b32_e32 v107, 0xffff0000, v77
	v_fma_f32 v98, -v20, v106, v98
	v_fma_f32 v99, -v20, v107, v99
	v_lshlrev_b32_e32 v100, 16, v74
	v_and_b32_e32 v101, 0xffff0000, v74
	v_lshlrev_b32_e32 v106, 16, v78
	v_and_b32_e32 v107, 0xffff0000, v78
	v_fma_f32 v100, -v20, v106, v100
	v_fma_f32 v101, -v20, v107, v101
	v_lshlrev_b32_e32 v102, 16, v75
	v_and_b32_e32 v103, 0xffff0000, v75
	v_lshlrev_b32_e32 v106, 16, v79
	v_and_b32_e32 v107, 0xffff0000, v79
	v_fma_f32 v102, -v20, v106, v102
	v_fma_f32 v103, -v20, v107, v103
	v_mul_f32_e32 v104, v96, v96
	v_fmac_f32_e32 v104, v97, v97
	v_fmac_f32_e32 v104, v98, v98
	v_fmac_f32_e32 v104, v99, v99
	v_fmac_f32_e32 v104, v100, v100
	v_fmac_f32_e32 v104, v101, v101
	v_fmac_f32_e32 v104, v102, v102
	v_fmac_f32_e32 v104, v103, v103
	s_nop 1
	v_add_f32_dpp v104, v104, v104 quad_perm:[1,0,3,2] row_mask:0xf bank_mask:0xf bound_ctrl:1
	s_nop 1
	v_add_f32_dpp v104, v104, v104 quad_perm:[2,3,0,1] row_mask:0xf bank_mask:0xf bound_ctrl:1
	s_nop 1
	v_add_f32_dpp v104, v104, v104 row_ror:4 row_mask:0xf bank_mask:0xf bound_ctrl:1
	s_nop 1
	v_add_f32_dpp v104, v104, v104 row_ror:8 row_mask:0xf bank_mask:0xf bound_ctrl:1
	v_mov_b32_e32 v105, 0x358637bd
	v_fmac_f32_e32 v105, 0x3c000000, v104
	v_rsq_f32_e32 v105, v105
	s_nop 0
	v_mul_f32_e32 v108, v96, v105
	v_mul_f32_e32 v108, v108, v4
	v_mul_f32_e32 v109, v97, v105
	v_mul_f32_e32 v109, v109, v5
	v_mul_f32_e32 v110, v98, v105
	v_mul_f32_e32 v110, v110, v6
	v_mul_f32_e32 v111, v99, v105
	v_mul_f32_e32 v111, v111, v7
	v_mul_f32_e32 v112, v100, v105
	v_mul_f32_e32 v112, v112, v8
	v_mul_f32_e32 v113, v101, v105
	v_mul_f32_e32 v113, v113, v9
	v_mul_f32_e32 v114, v102, v105
	v_mul_f32_e32 v114, v114, v10
	v_mul_f32_e32 v115, v103, v105
	v_mul_f32_e32 v115, v115, v11
	v_cvt_pk_bf16_f32 v120, v108, v109
	v_cvt_pk_bf16_f32 v121, v110, v111
	v_cvt_pk_bf16_f32 v122, v112, v113
	v_cvt_pk_bf16_f32 v123, v114, v115
	global_store_dwordx4 v30, v[120:123], s[14:15]
	s_nop 1
	v_lshlrev_b32_e32 v106, 16, v80
	v_and_b32_e32 v107, 0xffff0000, v80
	v_lshlrev_b32_e32 v96, 16, v84
	v_and_b32_e32 v97, 0xffff0000, v84
	v_add_f32_e32 v96, v106, v96
	v_add_f32_e32 v97, v107, v97
	v_lshlrev_b32_e32 v106, 16, v81
	v_and_b32_e32 v107, 0xffff0000, v81
	v_lshlrev_b32_e32 v98, 16, v85
	v_and_b32_e32 v99, 0xffff0000, v85
	v_add_f32_e32 v98, v106, v98
	v_add_f32_e32 v99, v107, v99
	v_lshlrev_b32_e32 v106, 16, v82
	v_and_b32_e32 v107, 0xffff0000, v82
	v_lshlrev_b32_e32 v100, 16, v86
	v_and_b32_e32 v101, 0xffff0000, v86
	v_add_f32_e32 v100, v106, v100
	v_add_f32_e32 v101, v107, v101
	v_lshlrev_b32_e32 v106, 16, v83
	v_and_b32_e32 v107, 0xffff0000, v83
	v_lshlrev_b32_e32 v102, 16, v87
	v_and_b32_e32 v103, 0xffff0000, v87
	v_add_f32_e32 v102, v106, v102
	v_add_f32_e32 v103, v107, v103
	v_mul_f32_e32 v104, v96, v96
	v_fmac_f32_e32 v104, v97, v97
	v_fmac_f32_e32 v104, v98, v98
	v_fmac_f32_e32 v104, v99, v99
	v_fmac_f32_e32 v104, v100, v100
	v_fmac_f32_e32 v104, v101, v101
	v_fmac_f32_e32 v104, v102, v102
	v_fmac_f32_e32 v104, v103, v103
	s_nop 1
	v_add_f32_dpp v104, v104, v104 quad_perm:[1,0,3,2] row_mask:0xf bank_mask:0xf bound_ctrl:1
	s_nop 1
	v_add_f32_dpp v104, v104, v104 quad_perm:[2,3,0,1] row_mask:0xf bank_mask:0xf bound_ctrl:1
	s_nop 1
	v_add_f32_dpp v104, v104, v104 row_ror:4 row_mask:0xf bank_mask:0xf bound_ctrl:1
	s_nop 1
	v_add_f32_dpp v104, v104, v104 row_ror:8 row_mask:0xf bank_mask:0xf bound_ctrl:1
	v_mov_b32_e32 v105, 0x358637bd
	v_fmac_f32_e32 v105, 0x3c000000, v104
	v_rsq_f32_e32 v105, v105
	s_nop 0
	v_lshlrev_b32_e32 v106, 16, v88
	v_and_b32_e32 v107, 0xffff0000, v88
	v_mul_f32_e32 v108, v96, v105
	v_mul_f32_e32 v108, v12, v108
	v_mul_f32_e32 v108, v108, v106
	v_mul_f32_e32 v109, v97, v105
	v_mul_f32_e32 v109, v13, v109
	v_mul_f32_e32 v109, v109, v107
	v_lshlrev_b32_e32 v106, 16, v89
	v_and_b32_e32 v107, 0xffff0000, v89
	v_mul_f32_e32 v110, v98, v105
	v_mul_f32_e32 v110, v14, v110
	v_mul_f32_e32 v110, v110, v106
	v_mul_f32_e32 v111, v99, v105
	v_mul_f32_e32 v111, v15, v111
	v_mul_f32_e32 v111, v111, v107
	v_lshlrev_b32_e32 v106, 16, v90
	v_and_b32_e32 v107, 0xffff0000, v90
	v_mul_f32_e32 v112, v100, v105
	v_mul_f32_e32 v112, v16, v112
	v_mul_f32_e32 v112, v112, v106
	v_mul_f32_e32 v113, v101, v105
	v_mul_f32_e32 v113, v17, v113
	v_mul_f32_e32 v113, v113, v107
	v_lshlrev_b32_e32 v106, 16, v91
	v_and_b32_e32 v107, 0xffff0000, v91
	v_mul_f32_e32 v114, v102, v105
	v_mul_f32_e32 v114, v18, v114
	v_mul_f32_e32 v114, v114, v106
	v_mul_f32_e32 v115, v103, v105
	v_mul_f32_e32 v115, v19, v115
	v_mul_f32_e32 v115, v115, v107
	v_cvt_pk_bf16_f32 v124, v108, v109
	v_cvt_pk_bf16_f32 v125, v110, v111
	v_cvt_pk_bf16_f32 v126, v112, v113
	v_cvt_pk_bf16_f32 v127, v114, v115
	global_store_dwordx4 v30, v[124:127], s[14:15] offset:1024
	s_nop 1
	s_add_i32 s17, s17, 1
	s_cmp_lt_u32 s17, 3
	s_cbranch_scc1 .Lcmb_odd_loop
	s_movk_i32 s79, 0x40ff
	s_movk_i32 s78, 0x2000
	s_mov_b64 s[4:5], exec

; __device__ __forceinline__ int tid_() { int t = threadIdx.x; asm volatile("" : "+v"(t)); return t; }
; __device__ __forceinline__ float bf2f(bf16_t b) { return __uint_as_float(((unsigned)b) << 16); }
; __device__ __forceinline__ bf16_t f2bf(float f) { return (bf16_t)(cvt_pk_bf16(f, 0.f) & 0xffffu); }
; __device__ __forceinline__ void rec_combine(const bf16_t* __restrict__ OF, const bf16_t* __restrict__ OBk, const bf16_t* __restrict__ gate, const float* __restrict__ nw, bf16_t* __restrict__ Y, int coff) {
;   const int tid = tid_(); const int wid = tid >> 6, lane = tid & 63; const float w0 = nw[lane], w1 = nw[64 + lane];
;   const int stride = gridDim.x * 8;
;   for (int r0 = blockIdx.x * 8 + wid; r0 < T_TOK; r0 += 2 * stride)
; #pragma unroll
;   for (int rr = 0; rr < 2; ++rr) { const int r = r0 + rr * stride; if (r >= T_TOK) break;
; #pragma unroll
;     for (int h = 0; h < 4; ++h) { const size_t b = (size_t)r * 512 + h * 128 + lane;
;       const float a0 = bf2f(OF[b]) + bf2f(OBk[b]), a1 = bf2f(OF[b + 64]) + bf2f(OBk[b + 64]);
;       const float ss = wave_sum(a0 * a0 + a1 * a1); const float rs = rsqrtf(ss * (1.f / 128.f) + EPSN);
;       bf16_t* yo = Y + (size_t)r * DM + coff + h * 128 + lane; yo[0] = f2bf(a0 * rs * w0 * bf2f(gate[b])); yo[64] = f2bf(a1 * rs * w1 * bf2f(gate[b + 64])); }
;   }
; }
.LBB0_2327:
	s_or_b64 exec, exec, s[4:5]
	s_mov_b64 s[12:13], s[0:1]
	s_mov_b64 s[8:9], s[0:1]
	s_mov_b64 s[6:7], s[0:1]
	s_mov_b64 s[10:11], s[0:1]
	s_waitcnt lgkmcnt(0)
	v_mov_b32_e32 v0, v187
	s_barrier
	s_load_dwordx2 s[4:5], s[0:1], 0xd8
	s_load_dwordx2 s[10:11], s[0:1], 0x60
	v_and_b32_e32 v0, 63, v187
	v_lshlrev_b32_e32 v1, 4, v0
	v_and_b32_e32 v2, 15, v0
	v_lshlrev_b32_e32 v2, 5, v2
	s_lshl_b32 s16, s34, 9
	v_add_u32_e32 v2, s16, v2
	v_readfirstlane_b32 s17, v187
	s_nop 3
	s_lshr_b32 s17, s17, 6
	s_lshl_b32 s16, s2, 3
	s_add_i32 s16, s16, s17
	s_waitcnt lgkmcnt(0)
	global_load_dwordx4 v[12:15], v2, s[10:11]
	global_load_dwordx4 v[16:19], v2, s[10:11] offset:16
	s_add_u32 s8, s4, 0x4100000
	s_addc_u32 s9, s5, 0
	s_add_u32 s10, s4, 0x5140000
	s_addc_u32 s11, s5, 0
	s_add_u32 s12, s4, 0x1158e100
	s_addc_u32 s13, s5, 0
	s_add_u32 s14, s4, 0x6180000
	s_addc_u32 s15, s5, 0
	s_waitcnt vmcnt(0)
	s_mov_b32 s17, 0
.Lcmb_even_loop:
	s_min_i32 s4, s16, 0x40ff
	s_lshl_b32 s5, s4, 11
	v_add_u32_e32 v24, s5, v1
	s_lshl_b32 s5, s4, 10
	v_add_u32_e32 v23, s5, v1
	s_add_i32 s16, s16, 0x800
	global_load_dwordx4 v[40:43], v23, s[8:9]
	global_load_dwordx4 v[44:47], v23, s[10:11]
	global_load_dwordx4 v[48:51], v23, s[12:13]
	s_min_i32 s4, s16, 0x40ff
	s_lshl_b32 s5, s4, 11
	v_add_u32_e32 v27, s5, v1
	s_lshl_b32 s5, s4, 10
	v_add_u32_e32 v26, s5, v1
	s_add_i32 s16, s16, 0x800
	global_load_dwordx4 v[60:63], v26, s[8:9]
	global_load_dwordx4 v[64:67], v26, s[10:11]
	global_load_dwordx4 v[68:71], v26, s[12:13]
	s_min_i32 s4, s16, 0x40ff
	s_lshl_b32 s5, s4, 11
	v_add_u32_e32 v30, s5, v1
	s_lshl_b32 s5, s4, 10
	v_add_u32_e32 v29, s5, v1
	s_add_i32 s16, s16, 0x800
	global_load_dwordx4 v[80:83], v29, s[8:9]
	global_load_dwordx4 v[84:87], v29, s[10:11]
	global_load_dwordx4 v[88:91], v29, s[12:13]
	s_waitcnt vmcnt(6)
	v_lshlrev_b32_e32 v106, 16, v40
	v_and_b32_e32 v107, 0xffff0000, v40
	v_lshlrev_b32_e32 v96, 16, v44
	v_and_b32_e32 v97, 0xffff0000, v44
	v_add_f32_e32 v96, v106, v96
	v_add_f32_e32 v97, v107, v97
	v_lshlrev_b32_e32 v106, 16, v41
	v_and_b32_e32 v107, 0xffff0000, v41
	v_lshlrev_b32_e32 v98, 16, v45
	v_and_b32_e32 v99, 0xffff0000, v45
	v_add_f32_e32 v98, v106, v98
	v_add_f32_e32 v99, v107, v99
	v_lshlrev_b32_e32 v106, 16, v42
	v_and_b32_e32 v107, 0xffff0000, v42
	v_lshlrev_b32_e32 v100, 16, v46
	v_and_b32_e32 v101, 0xffff0000, v46
	v_add_f32_e32 v100, v106, v100
	v_add_f32_e32 v101, v107, v101
	v_lshlrev_b32_e32 v106, 16, v43
	v_and_b32_e32 v107, 0xffff0000, v43
	v_lshlrev_b32_e32 v102, 16, v47
	v_and_b32_e32 v103, 0xffff0000, v47
	v_add_f32_e32 v102, v106, v102
	v_add_f32_e32 v103, v107, v103
	v_mul_f32_e32 v104, v96, v96
	v_fmac_f32_e32 v104, v97, v97
	v_fmac_f32_e32 v104, v98, v98
	v_fmac_f32_e32 v104, v99, v99
	v_fmac_f32_e32 v104, v100, v100
	v_fmac_f32_e32 v104, v101, v101
	v_fmac_f32_e32 v104, v102, v102
	v_fmac_f32_e32 v104, v103, v103
	s_nop 1
	v_add_f32_dpp v104, v104, v104 quad_perm:[1,0,3,2] row_mask:0xf bank_mask:0xf bound_ctrl:1
	s_nop 1
	v_add_f32_dpp v104, v104, v104 quad_perm:[2,3,0,1] row_mask:0xf bank_mask:0xf bound_ctrl:1
	s_nop 1
	v_add_f32_dpp v104, v104, v104 row_ror:4 row_mask:0xf bank_mask:0xf bound_ctrl:1
	s_nop 1
	v_add_f32_dpp v104, v104, v104 row_ror:8 row_mask:0xf bank_mask:0xf bound_ctrl:1
	v_mov_b32_e32 v105, 0x358637bd
	v_fmac_f32_e32 v105, 0x3c000000, v104
	v_rsq_f32_e32 v105, v105
	s_nop 0
	v_lshlrev_b32_e32 v106, 16, v48
	v_and_b32_e32 v107, 0xffff0000, v48
	v_mul_f32_e32 v108, v96, v105
	v_mul_f32_e32 v108, v12, v108
	v_mul_f32_e32 v108, v108, v106
	v_mul_f32_e32 v109, v97, v105
	v_mul_f32_e32 v109, v13, v109
	v_mul_f32_e32 v109, v109, v107
	v_lshlrev_b32_e32 v106, 16, v49
	v_and_b32_e32 v107, 0xffff0000, v49
	v_mul_f32_e32 v110, v98, v105
	v_mul_f32_e32 v110, v14, v110
	v_mul_f32_e32 v110, v110, v106
	v_mul_f32_e32 v111, v99, v105
	v_mul_f32_e32 v111, v15, v111
	v_mul_f32_e32 v111, v111, v107
	v_lshlrev_b32_e32 v106, 16, v50
	v_and_b32_e32 v107, 0xffff0000, v50
	v_mul_f32_e32 v112, v100, v105
	v_mul_f32_e32 v112, v16, v112
	v_mul_f32_e32 v112, v112, v106
	v_mul_f32_e32 v113, v101, v105
	v_mul_f32_e32 v113, v17, v113
	v_mul_f32_e32 v113, v113, v107
	v_lshlrev_b32_e32 v106, 16, v51
	v_and_b32_e32 v107, 0xffff0000, v51
	v_mul_f32_e32 v114, v102, v105
	v_mul_f32_e32 v114, v18, v114
	v_mul_f32_e32 v114, v114, v106
	v_mul_f32_e32 v115, v103, v105
	v_mul_f32_e32 v115, v19, v115
	v_mul_f32_e32 v115, v115, v107
	v_cvt_pk_bf16_f32 v124, v108, v109
	v_cvt_pk_bf16_f32 v125, v110, v111
	v_cvt_pk_bf16_f32 v126, v112, v113
	v_cvt_pk_bf16_f32 v127, v114, v115
	global_store_dwordx4 v24, v[124:127], s[14:15] offset:0
	s_nop 1
	s_waitcnt vmcnt(4)
; __device__ __forceinline__ int tid_() { int t = threadIdx.x; asm volatile("" : "+v"(t)); return t; }
; __device__ __forceinline__ float bf2f(bf16_t b) { return __uint_as_float(((unsigned)b) << 16); }
; __device__ __forceinline__ bf16_t f2bf(float f) { return (bf16_t)(cvt_pk_bf16(f, 0.f) & 0xffffu); }
; __device__ __forceinline__ void rec_combine(const bf16_t* __restrict__ OF, const bf16_t* __restrict__ OBk, const bf16_t* __restrict__ gate, const float* __restrict__ nw, bf16_t* __restrict__ Y, int coff) {
;   const int tid = tid_(); const int wid = tid >> 6, lane = tid & 63; const float w0 = nw[lane], w1 = nw[64 + lane];
;   const int stride = gridDim.x * 8;
;   for (int r0 = blockIdx.x * 8 + wid; r0 < T_TOK; r0 += 2 * stride)
; #pragma unroll
;   for (int rr = 0; rr < 2; ++rr) { const int r = r0 + rr * stride; if (r >= T_TOK) break;
; #pragma unroll
;     for (int h = 0; h < 4; ++h) { const size_t b = (size_t)r * 512 + h * 128 + lane;
;       const float a0 = bf2f(OF[b]) + bf2f(OBk[b]), a1 = bf2f(OF[b + 64]) + bf2f(OBk[b + 64]);
;       const float ss = wave_sum(a0 * a0 + a1 * a1); const float rs = rsqrtf(ss * (1.f / 128.f) + EPSN);
;       bf16_t* yo = Y + (size_t)r * DM + coff + h * 128 + lane; yo[0] = f2bf(a0 * rs * w0 * bf2f(gate[b])); yo[64] = f2bf(a1 * rs * w1 * bf2f(gate[b + 64])); }
;   }
; }
	v_lshlrev_b32_e32 v106, 16, v60
	v_and_b32_e32 v107, 0xffff0000, v60
	v_lshlrev_b32_e32 v96, 16, v64
	v_and_b32_e32 v97, 0xffff0000, v64
	v_add_f32_e32 v96, v106, v96
	v_add_f32_e32 v97, v107, v97
	v_lshlrev_b32_e32 v106, 16, v61
	v_and_b32_e32 v107, 0xffff0000, v61
	v_lshlrev_b32_e32 v98, 16, v65
	v_and_b32_e32 v99, 0xffff0000, v65
	v_add_f32_e32 v98, v106, v98
	v_add_f32_e32 v99, v107, v99
	v_lshlrev_b32_e32 v106, 16, v62
	v_and_b32_e32 v107, 0xffff0000, v62
	v_lshlrev_b32_e32 v100, 16, v66
	v_and_b32_e32 v101, 0xffff0000, v66
	v_add_f32_e32 v100, v106, v100
	v_add_f32_e32 v101, v107, v101
	v_lshlrev_b32_e32 v106, 16, v63
	v_and_b32_e32 v107, 0xffff0000, v63
	v_lshlrev_b32_e32 v102, 16, v67
	v_and_b32_e32 v103, 0xffff0000, v67
	v_add_f32_e32 v102, v106, v102
	v_add_f32_e32 v103, v107, v103
	v_mul_f32_e32 v104, v96, v96
	v_fmac_f32_e32 v104, v97, v97
	v_fmac_f32_e32 v104, v98, v98
	v_fmac_f32_e32 v104, v99, v99
	v_fmac_f32_e32 v104, v100, v100
	v_fmac_f32_e32 v104, v101, v101
	v_fmac_f32_e32 v104, v102, v102
	v_fmac_f32_e32 v104, v103, v103
	s_nop 1
	v_add_f32_dpp v104, v104, v104 quad_perm:[1,0,3,2] row_mask:0xf bank_mask:0xf bound_ctrl:1
	s_nop 1
	v_add_f32_dpp v104, v104, v104 quad_perm:[2,3,0,1] row_mask:0xf bank_mask:0xf bound_ctrl:1
	s_nop 1
	v_add_f32_dpp v104, v104, v104 row_ror:4 row_mask:0xf bank_mask:0xf bound_ctrl:1
	s_nop 1
	v_add_f32_dpp v104, v104, v104 row_ror:8 row_mask:0xf bank_mask:0xf bound_ctrl:1
	v_mov_b32_e32 v105, 0x358637bd
	v_fmac_f32_e32 v105, 0x3c000000, v104
	v_rsq_f32_e32 v105, v105
	s_nop 0
	v_lshlrev_b32_e32 v106, 16, v68
	v_and_b32_e32 v107, 0xffff0000, v68
	v_mul_f32_e32 v108, v96, v105
	v_mul_f32_e32 v108, v12, v108
	v_mul_f32_e32 v108, v108, v106
	v_mul_f32_e32 v109, v97, v105
	v_mul_f32_e32 v109, v13, v109
	v_mul_f32_e32 v109, v109, v107
	v_lshlrev_b32_e32 v106, 16, v69
	v_and_b32_e32 v107, 0xffff0000, v69
	v_mul_f32_e32 v110, v98, v105
	v_mul_f32_e32 v110, v14, v110
	v_mul_f32_e32 v110, v110, v106
	v_mul_f32_e32 v111, v99, v105
	v_mul_f32_e32 v111, v15, v111
	v_mul_f32_e32 v111, v111, v107
	v_lshlrev_b32_e32 v106, 16, v70
	v_and_b32_e32 v107, 0xffff0000, v70
	v_mul_f32_e32 v112, v100, v105
	v_mul_f32_e32 v112, v16, v112
	v_mul_f32_e32 v112, v112, v106
	v_mul_f32_e32 v113, v101, v105
	v_mul_f32_e32 v113, v17, v113
	v_mul_f32_e32 v113, v113, v107
	v_lshlrev_b32_e32 v106, 16, v71
	v_and_b32_e32 v107, 0xffff0000, v71
	v_mul_f32_e32 v114, v102, v105
	v_mul_f32_e32 v114, v18, v114
	v_mul_f32_e32 v114, v114, v106
	v_mul_f32_e32 v115, v103, v105
	v_mul_f32_e32 v115, v19, v115
	v_mul_f32_e32 v115, v115, v107
	v_cvt_pk_bf16_f32 v124, v108, v109
	v_cvt_pk_bf16_f32 v125, v110, v111
	v_cvt_pk_bf16_f32 v126, v112, v113
	v_cvt_pk_bf16_f32 v127, v114, v115
	global_store_dwordx4 v27, v[124:127], s[14:15] offset:0
	s_nop 1
	s_waitcnt vmcnt(2)
	v_lshlrev_b32_e32 v106, 16, v80
	v_and_b32_e32 v107, 0xffff0000, v80
	v_lshlrev_b32_e32 v96, 16, v84
	v_and_b32_e32 v97, 0xffff0000, v84
	v_add_f32_e32 v96, v106, v96
	v_add_f32_e32 v97, v107, v97
	v_lshlrev_b32_e32 v106, 16, v81
	v_and_b32_e32 v107, 0xffff0000, v81
	v_lshlrev_b32_e32 v98, 16, v85
	v_and_b32_e32 v99, 0xffff0000, v85
	v_add_f32_e32 v98, v106, v98
	v_add_f32_e32 v99, v107, v99
	v_lshlrev_b32_e32 v106, 16, v82
	v_and_b32_e32 v107, 0xffff0000, v82
	v_lshlrev_b32_e32 v100, 16, v86
	v_and_b32_e32 v101, 0xffff0000, v86
	v_add_f32_e32 v100, v106, v100
	v_add_f32_e32 v101, v107, v101
	v_lshlrev_b32_e32 v106, 16, v83
	v_and_b32_e32 v107, 0xffff0000, v83
	v_lshlrev_b32_e32 v102, 16, v87
	v_and_b32_e32 v103, 0xffff0000, v87
	v_add_f32_e32 v102, v106, v102
	v_add_f32_e32 v103, v107, v103
	v_mul_f32_e32 v104, v96, v96
	v_fmac_f32_e32 v104, v97, v97
	v_fmac_f32_e32 v104, v98, v98
	v_fmac_f32_e32 v104, v99, v99
	v_fmac_f32_e32 v104, v100, v100
	v_fmac_f32_e32 v104, v101, v101
	v_fmac_f32_e32 v104, v102, v102
	v_fmac_f32_e32 v104, v103, v103
	s_nop 1
	v_add_f32_dpp v104, v104, v104 quad_perm:[1,0,3,2] row_mask:0xf bank_mask:0xf bound_ctrl:1
	s_nop 1
	v_add_f32_dpp v104, v104, v104 quad_perm:[2,3,0,1] row_mask:0xf bank_mask:0xf bound_ctrl:1
	s_nop 1
	v_add_f32_dpp v104, v104, v104 row_ror:4 row_mask:0xf bank_mask:0xf bound_ctrl:1
	s_nop 1
	v_add_f32_dpp v104, v104, v104 row_ror:8 row_mask:0xf bank_mask:0xf bound_ctrl:1
	v_mov_b32_e32 v105, 0x358637bd
	v_fmac_f32_e32 v105, 0x3c000000, v104
	v_rsq_f32_e32 v105, v105
	s_nop 0
	v_lshlrev_b32_e32 v106, 16, v88
	v_and_b32_e32 v107, 0xffff0000, v88
	v_mul_f32_e32 v108, v96, v105
	v_mul_f32_e32 v108, v12, v108
	v_mul_f32_e32 v108, v108, v106
	v_mul_f32_e32 v109, v97, v105
	v_mul_f32_e32 v109, v13, v109
	v_mul_f32_e32 v109, v109, v107
	v_lshlrev_b32_e32 v106, 16, v89
	v_and_b32_e32 v107, 0xffff0000, v89
	v_mul_f32_e32 v110, v98, v105
	v_mul_f32_e32 v110, v14, v110
	v_mul_f32_e32 v110, v110, v106
	v_mul_f32_e32 v111, v99, v105
	v_mul_f32_e32 v111, v15, v111
	v_mul_f32_e32 v111, v111, v107
	v_lshlrev_b32_e32 v106, 16, v90
	v_and_b32_e32 v107, 0xffff0000, v90
	v_mul_f32_e32 v112, v100, v105
	v_mul_f32_e32 v112, v16, v112
	v_mul_f32_e32 v112, v112, v106
	v_mul_f32_e32 v113, v101, v105
	v_mul_f32_e32 v113, v17, v113
	v_mul_f32_e32 v113, v113, v107
	v_lshlrev_b32_e32 v106, 16, v91
	v_and_b32_e32 v107, 0xffff0000, v91
	v_mul_f32_e32 v114, v102, v105
	v_mul_f32_e32 v114, v18, v114
	v_mul_f32_e32 v114, v114, v106
	v_mul_f32_e32 v115, v103, v105
	v_mul_f32_e32 v115, v19, v115
	v_mul_f32_e32 v115, v115, v107
	v_cvt_pk_bf16_f32 v124, v108, v109
	v_cvt_pk_bf16_f32 v125, v110, v111
	v_cvt_pk_bf16_f32 v126, v112, v113
	v_cvt_pk_bf16_f32 v127, v114, v115
	global_store_dwordx4 v30, v[124:127], s[14:15] offset:0
	s_nop 1
	s_add_i32 s17, s17, 1
	s_cmp_lt_u32 s17, 3
	s_cbranch_scc1 .Lcmb_even_loop
	s_mov_b64 s[4:5], exec
